# weight-conversion transposes: the 16 transposed LDS reads of an item issued together into fresh VGPRs (was read-wait-convert one by one)
# speedup vs baseline: 1.0046x; 1.0046x over previous
; __device__ __forceinline__ unsigned cvt_pk_bf16(float lo, float hi) { unsigned r; asm volatile("v_cvt_pk_bf16_f32 %0, %1, %2" : "=v"(r) : "v"(lo), "v"(hi)); return r; }
; template <int MAP>
; __device__ __forceinline__ void transpose_item(const float* __restrict__ W, int K, int N, bf16_t* __restrict__ WT, float* scr, int item, int lane) {
;     ...
;     const int c = lane & 7;
; #pragma unroll
;     for (int j = 0; j < 4; ++j) { const int n = (lane >> 3) + 8 * j; const float* s = scr + (8 * c) * 33 + n;
;         u32x4 o; o.x = cvt_pk_bf16(s[0 * 33], s[1 * 33]); o.y = cvt_pk_bf16(s[2 * 33], s[3 * 33]); o.z = cvt_pk_bf16(s[4 * 33], s[5 * 33]); o.w = cvt_pk_bf16(s[6 * 33], s[7 * 33]);
;         if (MAP == 1) *(u32x4*)(WT + (size_t)row_map<MAP>(n0 + n) * K + k0 + 8 * c) = o;
;         else __builtin_nontemporal_store(o, (u32x4*)(WT + (size_t)row_map<MAP>(n0 + n) * K + k0 + 8 * c)); }
.LBB0_42:
	v_lshl_add_u64 v[70:71], v[44:45], 0, s[8:9]
	v_lshl_add_u64 v[72:73], v[42:43], 0, s[8:9]
	v_lshl_add_u64 v[74:75], v[40:41], 0, s[8:9]
	v_lshl_add_u64 v[76:77], v[38:39], 0, s[8:9]
	v_lshl_add_u64 v[78:79], v[36:37], 0, s[8:9]
	v_lshl_add_u64 v[80:81], v[34:35], 0, s[8:9]
	v_lshl_add_u64 v[82:83], v[2:3], 0, s[8:9]
	v_lshl_add_u64 v[84:85], v[0:1], 0, s[8:9]
	global_load_dword v69, v[70:71], off nt
	global_load_dword v86, v[72:73], off nt
	global_load_dword v87, v[74:75], off nt
	global_load_dword v88, v[76:77], off nt
	global_load_dword v89, v[78:79], off nt
	global_load_dword v90, v[80:81], off nt
	global_load_dword v91, v[82:83], off nt
	global_load_dword v92, v[84:85], off nt
	s_add_u32 s8, s8, 0x20000
	s_addc_u32 s9, s9, 0
	v_add_u32_e32 v70, 0x400, v6
	s_cmp_lg_u32 s8, 0x80000
	v_lshl_add_u64 v[130:131], v[44:45], 0, s[8:9]
	v_lshl_add_u64 v[132:133], v[42:43], 0, s[8:9]
	v_lshl_add_u64 v[134:135], v[40:41], 0, s[8:9]
	v_lshl_add_u64 v[136:137], v[38:39], 0, s[8:9]
	v_lshl_add_u64 v[138:139], v[36:37], 0, s[8:9]
	v_lshl_add_u64 v[140:141], v[34:35], 0, s[8:9]
	v_lshl_add_u64 v[142:143], v[2:3], 0, s[8:9]
	v_lshl_add_u64 v[144:145], v[0:1], 0, s[8:9]
	global_load_dword v129, v[130:131], off nt
	global_load_dword v146, v[132:133], off nt
	global_load_dword v147, v[134:135], off nt
	global_load_dword v148, v[136:137], off nt
	global_load_dword v149, v[138:139], off nt
	global_load_dword v150, v[140:141], off nt
	global_load_dword v151, v[142:143], off nt
	global_load_dword v152, v[144:145], off nt
	s_add_u32 s8, s8, 0x20000
	s_addc_u32 s9, s9, 0
	v_add_u32_e32 v130, 0xc40, v6
	s_cmp_lg_u32 s8, 0x80000
	s_waitcnt vmcnt(14)
	ds_write2_b32 v6, v69, v86 offset1:66
	s_waitcnt vmcnt(12)
	ds_write2_b32 v6, v87, v88 offset0:132 offset1:198
	s_waitcnt vmcnt(10)
	ds_write2_b32 v70, v89, v90 offset0:8 offset1:74
	s_waitcnt vmcnt(8)
	ds_write2_b32 v70, v91, v92 offset0:140 offset1:206
	v_add_u32_e32 v6, 0x840, v6
	s_waitcnt vmcnt(6)
	ds_write2_b32 v6, v129, v146 offset1:66
	s_waitcnt vmcnt(4)
	ds_write2_b32 v6, v147, v148 offset0:132 offset1:198
	s_waitcnt vmcnt(2)
	ds_write2_b32 v130, v149, v150 offset0:8 offset1:74
	s_waitcnt vmcnt(0)
	ds_write2_b32 v130, v151, v152 offset0:140 offset1:206
	v_add_u32_e32 v6, 0x840, v6
	s_cbranch_scc1 .LBB0_42
	s_add_i32 s6, s27, 0xffffa200
	s_and_b32 s8, s6, 0x1fc0
	s_lshl_b32 s6, s6, 5
	s_waitcnt lgkmcnt(0)
	ds_read2_b32 v[96:97], v47 offset1:33
	ds_read2_b32 v[98:99], v47 offset0:66 offset1:99
	ds_read2_b32 v[100:101], v47 offset0:132 offset1:165
	ds_read2_b32 v[102:103], v47 offset0:198 offset1:231
	ds_read2_b32 v[104:105], v47 offset0:8 offset1:41
	ds_read2_b32 v[106:107], v47 offset0:74 offset1:107
	ds_read2_b32 v[108:109], v47 offset0:140 offset1:173
	ds_read2_b32 v[110:111], v47 offset0:206 offset1:239
	ds_read2_b32 v[112:113], v47 offset0:16 offset1:49
	ds_read2_b32 v[114:115], v47 offset0:82 offset1:115
	ds_read2_b32 v[116:117], v47 offset0:148 offset1:181
	ds_read2_b32 v[118:119], v47 offset0:214 offset1:247
	ds_read2_b32 v[120:121], v47 offset0:24 offset1:57
	ds_read2_b32 v[122:123], v47 offset0:90 offset1:123
	ds_read2_b32 v[124:125], v47 offset0:156 offset1:189
	ds_read2_b32 v[126:127], v47 offset0:222 offset1:255
	s_and_b32 s9, s6, 0x7e0
	s_nop 0
	v_or_b32_e32 v6, s9, v46
	s_waitcnt lgkmcnt(0)
	v_cvt_pk_bf16_f32 v0, v96, v97
	s_nop 0
	s_lshl_b32 s6, s8, 1
	v_mul_u32_u24_e32 v6, 0x1600, v6
	s_waitcnt lgkmcnt(0)
	v_cvt_pk_bf16_f32 v1, v98, v99
	s_nop 0
	v_lshl_add_u64 v[36:37], v[8:9], 0, s[6:7]
	v_lshlrev_b32_e32 v6, 1, v6
	s_waitcnt lgkmcnt(0)
	v_cvt_pk_bf16_f32 v2, v100, v101
	s_nop 0
	s_waitcnt lgkmcnt(0)
	v_cvt_pk_bf16_f32 v3, v102, v103
	v_lshl_add_u64 v[38:39], v[36:37], 0, v[6:7]
	v_or_b32_e32 v6, s9, v48
	s_nop 0
	global_store_dwordx4 v[38:39], v[0:3], off nt
	v_mul_u32_u24_e32 v6, 0x1600, v6
	v_lshlrev_b32_e32 v6, 1, v6
	s_waitcnt lgkmcnt(0)
	v_cvt_pk_bf16_f32 v0, v104, v105
	s_nop 0
	s_waitcnt lgkmcnt(0)
	v_cvt_pk_bf16_f32 v1, v106, v107
	s_nop 0
	s_waitcnt lgkmcnt(0)
	v_cvt_pk_bf16_f32 v2, v108, v109
	s_nop 0
	s_waitcnt lgkmcnt(0)
	v_cvt_pk_bf16_f32 v3, v110, v111
	v_lshl_add_u64 v[38:39], v[36:37], 0, v[6:7]
	v_or_b32_e32 v6, s9, v49
	s_nop 0
	global_store_dwordx4 v[38:39], v[0:3], off nt
	v_mul_u32_u24_e32 v6, 0x1600, v6
	v_lshlrev_b32_e32 v6, 1, v6
	s_waitcnt lgkmcnt(0)
	v_cvt_pk_bf16_f32 v0, v112, v113
	s_nop 0
	s_waitcnt lgkmcnt(0)
	v_cvt_pk_bf16_f32 v1, v114, v115
	s_nop 0
	s_waitcnt lgkmcnt(0)
	v_cvt_pk_bf16_f32 v2, v116, v117
	s_nop 0
	s_waitcnt lgkmcnt(0)
	v_cvt_pk_bf16_f32 v3, v118, v119
	v_lshl_add_u64 v[38:39], v[36:37], 0, v[6:7]
	s_nop 0
	global_store_dwordx4 v[38:39], v[0:3], off nt
	s_waitcnt lgkmcnt(0)
	s_nop 0
	v_cvt_pk_bf16_f32 v0, v120, v121
	s_nop 0
	s_waitcnt lgkmcnt(0)
	v_cvt_pk_bf16_f32 v1, v122, v123
	s_nop 0
	s_waitcnt lgkmcnt(0)
	v_cvt_pk_bf16_f32 v2, v124, v125
	v_or_b32_e32 v3, s9, v50
	v_mul_u32_u24_e32 v3, 0x1600, v3
	s_nop 0
	v_lshlrev_b32_e32 v6, 1, v3
	s_waitcnt lgkmcnt(0)
	v_cvt_pk_bf16_f32 v3, v126, v127
	v_lshl_add_u64 v[34:35], v[36:37], 0, v[6:7]
	global_store_dwordx4 v[34:35], v[0:3], off nt
	s_waitcnt lgkmcnt(0)
	s_mov_b64 s[8:9], 0

; __device__ __forceinline__ unsigned cvt_pk_bf16(float lo, float hi) { unsigned r; asm volatile("v_cvt_pk_bf16_f32 %0, %1, %2" : "=v"(r) : "v"(lo), "v"(hi)); return r; }
; template <int MAP>
; __device__ __forceinline__ int row_map(int n) {
;     ...
;     if (MAP == 2) { const int c = n < FF ? n : n - FF; return 256 * (c >> 7) + (c & 127) + (n < FF ? 0 : 128); }
; template <int MAP>
; __device__ __forceinline__ void transpose_item(const float* __restrict__ W, int K, int N, bf16_t* __restrict__ WT, float* scr, int item, int lane) {
;     ...
;     const int c = lane & 7;
; #pragma unroll
;     for (int j = 0; j < 4; ++j) { const int n = (lane >> 3) + 8 * j; const float* s = scr + (8 * c) * 33 + n;
;         u32x4 o; o.x = cvt_pk_bf16(s[0 * 33], s[1 * 33]); o.y = cvt_pk_bf16(s[2 * 33], s[3 * 33]); o.z = cvt_pk_bf16(s[4 * 33], s[5 * 33]); o.w = cvt_pk_bf16(s[6 * 33], s[7 * 33]);
;         if (MAP == 1) *(u32x4*)(WT + (size_t)row_map<MAP>(n0 + n) * K + k0 + 8 * c) = o;
;         else __builtin_nontemporal_store(o, (u32x4*)(WT + (size_t)row_map<MAP>(n0 + n) * K + k0 + 8 * c)); }
.LBB0_46:
	v_lshl_add_u64 v[42:43], v[40:41], 0, s[8:9]
	v_lshl_add_u64 v[44:45], v[38:39], 0, s[8:9]
	global_load_dword v69, v[42:43], off nt
	v_add_co_u32_e32 v42, vcc, 0x16000, v44
	v_lshl_add_u64 v[70:71], v[36:37], 0, s[8:9]
	s_nop 0
	v_addc_co_u32_e32 v43, vcc, 0, v45, vcc
	v_add_co_u32_e32 v78, vcc, 0x2c000, v44
	global_load_dword v80, v[42:43], off nt
	s_nop 0
	v_addc_co_u32_e32 v79, vcc, 0, v45, vcc
	v_add_co_u32_e32 v42, vcc, 0x42000, v44
	v_lshl_add_u64 v[72:73], v[34:35], 0, s[8:9]
	v_lshl_add_u64 v[74:75], v[2:3], 0, s[8:9]
	v_lshl_add_u64 v[76:77], v[0:1], 0, s[8:9]
	v_addc_co_u32_e32 v43, vcc, 0, v45, vcc
	global_load_dword v44, v[78:79], off nt
	global_load_dword v45, v[42:43], off nt
	global_load_dword v81, v[70:71], off nt
	global_load_dword v82, v[72:73], off nt
	global_load_dword v83, v[74:75], off nt
	global_load_dword v84, v[76:77], off nt
	s_add_u32 s8, s8, 0xb0000
	s_addc_u32 s9, s9, 0
	v_add_u32_e32 v42, 0x400, v6
	s_cmp_lg_u32 s8, 0x2c0000
	v_lshl_add_u64 v[102:103], v[40:41], 0, s[8:9]
	v_lshl_add_u64 v[104:105], v[38:39], 0, s[8:9]
	global_load_dword v129, v[102:103], off nt
	v_add_co_u32_e32 v102, vcc, 0x16000, v104
	v_lshl_add_u64 v[130:131], v[36:37], 0, s[8:9]
	s_nop 0
	v_addc_co_u32_e32 v103, vcc, 0, v105, vcc
	v_add_co_u32_e32 v138, vcc, 0x2c000, v104
	global_load_dword v140, v[102:103], off nt
	s_nop 0
	v_addc_co_u32_e32 v139, vcc, 0, v105, vcc
	v_add_co_u32_e32 v102, vcc, 0x42000, v104
	v_lshl_add_u64 v[132:133], v[34:35], 0, s[8:9]
	v_lshl_add_u64 v[134:135], v[2:3], 0, s[8:9]
	v_lshl_add_u64 v[136:137], v[0:1], 0, s[8:9]
	v_addc_co_u32_e32 v103, vcc, 0, v105, vcc
	global_load_dword v104, v[138:139], off nt
	global_load_dword v105, v[102:103], off nt
	global_load_dword v141, v[130:131], off nt
	global_load_dword v142, v[132:133], off nt
	global_load_dword v143, v[134:135], off nt
	global_load_dword v144, v[136:137], off nt
	s_add_u32 s8, s8, 0xb0000
	s_addc_u32 s9, s9, 0
	v_add_u32_e32 v102, 0xc40, v6
	s_cmp_lg_u32 s8, 0x2c0000
	s_waitcnt vmcnt(14)
	ds_write2_b32 v6, v69, v80 offset1:66
	s_waitcnt vmcnt(12)
	ds_write2_b32 v6, v44, v45 offset0:132 offset1:198
	s_waitcnt vmcnt(10)
	ds_write2_b32 v42, v81, v82 offset0:8 offset1:74
	s_waitcnt vmcnt(8)
	ds_write2_b32 v42, v83, v84 offset0:140 offset1:206
	v_add_u32_e32 v6, 0x840, v6
	s_waitcnt vmcnt(6)
	ds_write2_b32 v6, v129, v140 offset1:66
	s_waitcnt vmcnt(4)
	ds_write2_b32 v6, v104, v105 offset0:132 offset1:198
	s_waitcnt vmcnt(2)
	ds_write2_b32 v102, v141, v142 offset0:8 offset1:74
	s_waitcnt vmcnt(0)
	ds_write2_b32 v102, v143, v144 offset0:140 offset1:206
	v_add_u32_e32 v6, 0x840, v6
	s_cbranch_scc1 .LBB0_46
	s_waitcnt lgkmcnt(0)
	ds_read2_b32 v[96:97], v47 offset1:33
	ds_read2_b32 v[98:99], v47 offset0:66 offset1:99
	ds_read2_b32 v[100:101], v47 offset0:132 offset1:165
	ds_read2_b32 v[102:103], v47 offset0:198 offset1:231
	ds_read2_b32 v[104:105], v47 offset0:8 offset1:41
	ds_read2_b32 v[106:107], v47 offset0:74 offset1:107
	ds_read2_b32 v[108:109], v47 offset0:140 offset1:173
	ds_read2_b32 v[110:111], v47 offset0:206 offset1:239
	ds_read2_b32 v[112:113], v47 offset0:16 offset1:49
	ds_read2_b32 v[114:115], v47 offset0:82 offset1:115
	ds_read2_b32 v[116:117], v47 offset0:148 offset1:181
	ds_read2_b32 v[118:119], v47 offset0:214 offset1:247
	ds_read2_b32 v[120:121], v47 offset0:24 offset1:57
	ds_read2_b32 v[122:123], v47 offset0:90 offset1:123
	ds_read2_b32 v[124:125], v47 offset0:156 offset1:189
	ds_read2_b32 v[126:127], v47 offset0:222 offset1:255
	s_and_b32 s6, 0xffff, s11
	s_nop 0
	s_and_b32 s12, 0xffff, s12
	s_and_b32 s8, 0xffff, s10
	s_lshl_b32 s6, s6, 1
	s_waitcnt lgkmcnt(0)
	v_cvt_pk_bf16_f32 v0, v96, v97
	s_nop 0
	v_or_b32_e32 v6, s12, v46
	s_cmpk_lt_u32 s8, 0xb0
	s_waitcnt lgkmcnt(0)
	v_cvt_pk_bf16_f32 v1, v98, v99
	s_nop 0
	v_add_u32_e32 v38, 0xffffea00, v6
	s_cselect_b64 vcc, -1, 0
	s_waitcnt lgkmcnt(0)
	v_cvt_pk_bf16_f32 v2, v100, v101
	v_cndmask_b32_e32 v3, v38, v6, vcc
	v_lshlrev_b32_e32 v6, 1, v3
	s_and_b64 s[8:9], vcc, exec
	v_lshl_add_u64 v[34:35], v[10:11], 0, s[6:7]
	s_nop 0
	v_and_b32_e32 v38, 0x67, v3
	v_and_b32_e32 v6, 0xffffff00, v6
	s_cselect_b32 s6, 0, 0x80
	s_waitcnt lgkmcnt(0)
	v_cvt_pk_bf16_f32 v3, v102, v103
	v_or3_b32 v36, v38, v6, s6
	v_ashrrev_i32_e32 v37, 31, v36
	v_lshlrev_b64 v[36:37], 12, v[36:37]
	v_lshl_add_u64 v[36:37], v[34:35], 0, v[36:37]
	s_nop 0
	global_store_dwordx4 v[36:37], v[0:3], off nt
	v_or_b32_e32 v6, s12, v48
	s_waitcnt lgkmcnt(0)
	v_cvt_pk_bf16_f32 v0, v104, v105
	s_nop 0
	s_waitcnt lgkmcnt(0)
	v_cvt_pk_bf16_f32 v1, v106, v107
	s_nop 0
	s_waitcnt lgkmcnt(0)
	v_cvt_pk_bf16_f32 v2, v108, v109
	v_add_u32_e32 v3, 0xffffea00, v6
	v_cndmask_b32_e32 v6, v3, v6, vcc
	v_lshlrev_b32_e32 v3, 1, v6
	s_nop 0
	v_and_b32_e32 v38, 0xffffff00, v3
	v_and_b32_e32 v6, 0x6f, v6
	s_waitcnt lgkmcnt(0)
	v_cvt_pk_bf16_f32 v3, v110, v111
	v_or3_b32 v36, v6, v38, s6
	v_ashrrev_i32_e32 v37, 31, v36
	v_lshlrev_b64 v[36:37], 12, v[36:37]
	v_lshl_add_u64 v[36:37], v[34:35], 0, v[36:37]
	s_nop 0
	global_store_dwordx4 v[36:37], v[0:3], off nt
	v_or_b32_e32 v6, s12, v49
	s_waitcnt lgkmcnt(0)
	v_cvt_pk_bf16_f32 v0, v112, v113
	s_nop 0
	s_waitcnt lgkmcnt(0)
	v_cvt_pk_bf16_f32 v1, v114, v115
	s_nop 0
	v_add_u32_e32 v38, 0xffffea00, v6
	s_waitcnt lgkmcnt(0)
	v_cvt_pk_bf16_f32 v2, v116, v117
	v_cndmask_b32_e32 v3, v38, v6, vcc
	v_lshlrev_b32_e32 v6, 1, v3
	s_nop 0
	v_and_b32_e32 v38, 0x77, v3
	v_and_b32_e32 v6, 0xffffff00, v6
	s_waitcnt lgkmcnt(0)
	v_cvt_pk_bf16_f32 v3, v118, v119
	v_or3_b32 v36, v38, v6, s6
	v_ashrrev_i32_e32 v37, 31, v36
	v_lshlrev_b64 v[36:37], 12, v[36:37]
	v_lshl_add_u64 v[36:37], v[34:35], 0, v[36:37]
	v_or_b32_e32 v6, s12, v50
	s_nop 0
	global_store_dwordx4 v[36:37], v[0:3], off nt
	v_add_u32_e32 v36, 0xffffea00, v6
	v_cndmask_b32_e32 v6, v36, v6, vcc
	s_waitcnt lgkmcnt(0)
	v_cvt_pk_bf16_f32 v0, v120, v121
	s_nop 0
	s_waitcnt lgkmcnt(0)
	v_cvt_pk_bf16_f32 v1, v122, v123
	s_nop 0
	s_waitcnt lgkmcnt(0)
	v_cvt_pk_bf16_f32 v2, v124, v125
	v_lshlrev_b32_e32 v3, 1, v6
	v_and_b32_e32 v6, 0x7f, v6
	v_and_b32_e32 v3, 0xffffff00, v3
	v_or3_b32 v38, v6, v3, s6
	s_nop 0
	v_ashrrev_i32_e32 v39, 31, v38
	s_waitcnt lgkmcnt(0)
	v_cvt_pk_bf16_f32 v3, v126, v127
	v_lshlrev_b64 v[36:37], 12, v[38:39]
	v_lshl_add_u64 v[34:35], v[34:35], 0, v[36:37]
	global_store_dwordx4 v[34:35], v[0:3], off nt
	s_waitcnt lgkmcnt(0)

; __device__ __forceinline__ unsigned cvt_pk_bf16(float lo, float hi) { unsigned r; asm volatile("v_cvt_pk_bf16_f32 %0, %1, %2" : "=v"(r) : "v"(lo), "v"(hi)); return r; }
; template <int MAP>
; __device__ __forceinline__ void transpose_item(const float* __restrict__ W, int K, int N, bf16_t* __restrict__ WT, float* scr, int item, int lane) {
;     ...
;     const int c = lane & 7;
; #pragma unroll
;     for (int j = 0; j < 4; ++j) { const int n = (lane >> 3) + 8 * j; const float* s = scr + (8 * c) * 33 + n;
;         u32x4 o; o.x = cvt_pk_bf16(s[0 * 33], s[1 * 33]); o.y = cvt_pk_bf16(s[2 * 33], s[3 * 33]); o.z = cvt_pk_bf16(s[4 * 33], s[5 * 33]); o.w = cvt_pk_bf16(s[6 * 33], s[7 * 33]);
;         if (MAP == 1) *(u32x4*)(WT + (size_t)row_map<MAP>(n0 + n) * K + k0 + 8 * c) = o;
;         else __builtin_nontemporal_store(o, (u32x4*)(WT + (size_t)row_map<MAP>(n0 + n) * K + k0 + 8 * c)); }
.LBB0_51:
	v_lshl_add_u64 v[70:71], v[44:45], 0, s[8:9]
	v_lshl_add_u64 v[72:73], v[42:43], 0, s[8:9]
	v_lshl_add_u64 v[74:75], v[40:41], 0, s[8:9]
	v_lshl_add_u64 v[76:77], v[38:39], 0, s[8:9]
	v_lshl_add_u64 v[78:79], v[36:37], 0, s[8:9]
	v_lshl_add_u64 v[80:81], v[34:35], 0, s[8:9]
	v_lshl_add_u64 v[82:83], v[2:3], 0, s[8:9]
	v_lshl_add_u64 v[84:85], v[0:1], 0, s[8:9]
	global_load_dword v69, v[70:71], off nt
	global_load_dword v86, v[72:73], off nt
	global_load_dword v87, v[74:75], off nt
	global_load_dword v88, v[76:77], off nt
	global_load_dword v89, v[78:79], off nt
	global_load_dword v90, v[80:81], off nt
	global_load_dword v91, v[82:83], off nt
	global_load_dword v92, v[84:85], off nt
	s_add_u32 s8, s8, 0x20000
	s_addc_u32 s9, s9, 0
	v_add_u32_e32 v70, 0x400, v6
	s_cmp_lg_u32 s8, 0x80000
	v_lshl_add_u64 v[130:131], v[44:45], 0, s[8:9]
	v_lshl_add_u64 v[132:133], v[42:43], 0, s[8:9]
	v_lshl_add_u64 v[134:135], v[40:41], 0, s[8:9]
	v_lshl_add_u64 v[136:137], v[38:39], 0, s[8:9]
	v_lshl_add_u64 v[138:139], v[36:37], 0, s[8:9]
	v_lshl_add_u64 v[140:141], v[34:35], 0, s[8:9]
	v_lshl_add_u64 v[142:143], v[2:3], 0, s[8:9]
	v_lshl_add_u64 v[144:145], v[0:1], 0, s[8:9]
	global_load_dword v129, v[130:131], off nt
	global_load_dword v146, v[132:133], off nt
	global_load_dword v147, v[134:135], off nt
	global_load_dword v148, v[136:137], off nt
	global_load_dword v149, v[138:139], off nt
	global_load_dword v150, v[140:141], off nt
	global_load_dword v151, v[142:143], off nt
	global_load_dword v152, v[144:145], off nt
	s_add_u32 s8, s8, 0x20000
	s_addc_u32 s9, s9, 0
	v_add_u32_e32 v130, 0xc40, v6
	s_cmp_lg_u32 s8, 0x80000
	s_waitcnt vmcnt(14)
	ds_write2_b32 v6, v69, v86 offset1:66
	s_waitcnt vmcnt(12)
	ds_write2_b32 v6, v87, v88 offset0:132 offset1:198
	s_waitcnt vmcnt(10)
	ds_write2_b32 v70, v89, v90 offset0:8 offset1:74
	s_waitcnt vmcnt(8)
	ds_write2_b32 v70, v91, v92 offset0:140 offset1:206
	v_add_u32_e32 v6, 0x840, v6
	s_waitcnt vmcnt(6)
	ds_write2_b32 v6, v129, v146 offset1:66
	s_waitcnt vmcnt(4)
	ds_write2_b32 v6, v147, v148 offset0:132 offset1:198
	s_waitcnt vmcnt(2)
	ds_write2_b32 v130, v149, v150 offset0:8 offset1:74
	s_waitcnt vmcnt(0)
	ds_write2_b32 v130, v151, v152 offset0:140 offset1:206
	v_add_u32_e32 v6, 0x840, v6
	s_cbranch_scc1 .LBB0_51
	s_add_i32 s6, s27, 0xffffd600
	s_waitcnt lgkmcnt(0)
	ds_read2_b32 v[96:97], v47 offset1:33
	ds_read2_b32 v[98:99], v47 offset0:66 offset1:99
	ds_read2_b32 v[100:101], v47 offset0:132 offset1:165
	ds_read2_b32 v[102:103], v47 offset0:198 offset1:231
	ds_read2_b32 v[104:105], v47 offset0:8 offset1:41
	ds_read2_b32 v[106:107], v47 offset0:74 offset1:107
	ds_read2_b32 v[108:109], v47 offset0:140 offset1:173
	ds_read2_b32 v[110:111], v47 offset0:206 offset1:239
	ds_read2_b32 v[112:113], v47 offset0:16 offset1:49
	ds_read2_b32 v[114:115], v47 offset0:82 offset1:115
	ds_read2_b32 v[116:117], v47 offset0:148 offset1:181
	ds_read2_b32 v[118:119], v47 offset0:214 offset1:247
	ds_read2_b32 v[120:121], v47 offset0:24 offset1:57
	ds_read2_b32 v[122:123], v47 offset0:90 offset1:123
	ds_read2_b32 v[124:125], v47 offset0:156 offset1:189
	ds_read2_b32 v[126:127], v47 offset0:222 offset1:255
	s_and_b32 s8, s6, 0x1fc0
	s_lshl_b32 s6, s6, 5
	s_nop 0
	s_and_b32 s9, s6, 0x7e0
	s_waitcnt lgkmcnt(0)
	v_cvt_pk_bf16_f32 v0, v96, v97
	s_nop 0
	s_lshl_b32 s6, s8, 1
	v_or_b32_e32 v6, s9, v46
	s_waitcnt lgkmcnt(0)
	v_cvt_pk_bf16_f32 v1, v98, v99
	s_nop 0
	v_lshl_add_u64 v[36:37], v[12:13], 0, s[6:7]
	v_lshlrev_b32_e32 v6, 12, v6
	s_waitcnt lgkmcnt(0)
	v_cvt_pk_bf16_f32 v2, v100, v101
	s_nop 0
	s_waitcnt lgkmcnt(0)
	v_cvt_pk_bf16_f32 v3, v102, v103
	v_lshl_add_u64 v[38:39], v[36:37], 0, v[6:7]
	s_nop 0
	global_store_dwordx4 v[38:39], v[0:3], off nt
	v_or_b32_e32 v6, s9, v48
	v_lshlrev_b32_e32 v6, 12, v6
	s_waitcnt lgkmcnt(0)
	v_cvt_pk_bf16_f32 v0, v104, v105
	s_nop 0
	s_waitcnt lgkmcnt(0)
	v_cvt_pk_bf16_f32 v1, v106, v107
	s_nop 0
	s_waitcnt lgkmcnt(0)
	v_cvt_pk_bf16_f32 v2, v108, v109
	s_nop 0
	s_waitcnt lgkmcnt(0)
	v_cvt_pk_bf16_f32 v3, v110, v111
	v_lshl_add_u64 v[38:39], v[36:37], 0, v[6:7]
	s_nop 0
	global_store_dwordx4 v[38:39], v[0:3], off nt
	v_or_b32_e32 v6, s9, v49
	v_lshlrev_b32_e32 v6, 12, v6
	s_waitcnt lgkmcnt(0)
	v_cvt_pk_bf16_f32 v0, v112, v113
	s_nop 0
	s_waitcnt lgkmcnt(0)
	v_cvt_pk_bf16_f32 v1, v114, v115
	s_nop 0
	s_waitcnt lgkmcnt(0)
	v_cvt_pk_bf16_f32 v2, v116, v117
	s_nop 0
	s_waitcnt lgkmcnt(0)
	v_cvt_pk_bf16_f32 v3, v118, v119
	v_lshl_add_u64 v[38:39], v[36:37], 0, v[6:7]
	s_nop 0
	global_store_dwordx4 v[38:39], v[0:3], off nt
	s_waitcnt lgkmcnt(0)
	s_nop 0
	v_cvt_pk_bf16_f32 v0, v120, v121
	s_nop 0
	s_waitcnt lgkmcnt(0)
	v_cvt_pk_bf16_f32 v1, v122, v123
	s_nop 0
	s_waitcnt lgkmcnt(0)
	v_cvt_pk_bf16_f32 v2, v124, v125
	v_or_b32_e32 v3, s9, v50
	s_nop 0
	v_lshlrev_b32_e32 v6, 12, v3
	s_waitcnt lgkmcnt(0)
	v_cvt_pk_bf16_f32 v3, v126, v127
	v_lshl_add_u64 v[34:35], v[36:37], 0, v[6:7]
	global_store_dwordx4 v[34:35], v[0:3], off nt
	s_waitcnt lgkmcnt(0)

; __device__ __forceinline__ unsigned cvt_pk_bf16(float lo, float hi) { unsigned r; asm volatile("v_cvt_pk_bf16_f32 %0, %1, %2" : "=v"(r) : "v"(lo), "v"(hi)); return r; }
; template <int MAP>
; __device__ __forceinline__ void transpose_item(const float* __restrict__ W, int K, int N, bf16_t* __restrict__ WT, float* scr, int item, int lane) {
;     ...
;     const int c = lane & 7;
; #pragma unroll
;     for (int j = 0; j < 4; ++j) { const int n = (lane >> 3) + 8 * j; const float* s = scr + (8 * c) * 33 + n;
;         u32x4 o; o.x = cvt_pk_bf16(s[0 * 33], s[1 * 33]); o.y = cvt_pk_bf16(s[2 * 33], s[3 * 33]); o.z = cvt_pk_bf16(s[4 * 33], s[5 * 33]); o.w = cvt_pk_bf16(s[6 * 33], s[7 * 33]);
;         if (MAP == 1) *(u32x4*)(WT + (size_t)row_map<MAP>(n0 + n) * K + k0 + 8 * c) = o;
;         else __builtin_nontemporal_store(o, (u32x4*)(WT + (size_t)row_map<MAP>(n0 + n) * K + k0 + 8 * c)); }
.LBB0_56:
	v_lshl_add_u64 v[70:71], v[44:45], 0, s[8:9]
	v_lshl_add_u64 v[72:73], v[42:43], 0, s[8:9]
	v_lshl_add_u64 v[74:75], v[40:41], 0, s[8:9]
	v_lshl_add_u64 v[76:77], v[38:39], 0, s[8:9]
	v_lshl_add_u64 v[78:79], v[36:37], 0, s[8:9]
	v_lshl_add_u64 v[80:81], v[34:35], 0, s[8:9]
	v_lshl_add_u64 v[82:83], v[2:3], 0, s[8:9]
	v_lshl_add_u64 v[84:85], v[0:1], 0, s[8:9]
	global_load_dword v69, v[70:71], off nt
	global_load_dword v86, v[72:73], off nt
	global_load_dword v87, v[74:75], off nt
	global_load_dword v88, v[76:77], off nt
	global_load_dword v89, v[78:79], off nt
	global_load_dword v90, v[80:81], off nt
	global_load_dword v91, v[82:83], off nt
	global_load_dword v92, v[84:85], off nt
	s_add_u32 s8, s8, 0x20000
	s_addc_u32 s9, s9, 0
	v_add_u32_e32 v70, 0x400, v6
	s_cmp_lg_u32 s8, 0x80000
	v_lshl_add_u64 v[130:131], v[44:45], 0, s[8:9]
	v_lshl_add_u64 v[132:133], v[42:43], 0, s[8:9]
	v_lshl_add_u64 v[134:135], v[40:41], 0, s[8:9]
	v_lshl_add_u64 v[136:137], v[38:39], 0, s[8:9]
	v_lshl_add_u64 v[138:139], v[36:37], 0, s[8:9]
	v_lshl_add_u64 v[140:141], v[34:35], 0, s[8:9]
	v_lshl_add_u64 v[142:143], v[2:3], 0, s[8:9]
	v_lshl_add_u64 v[144:145], v[0:1], 0, s[8:9]
	global_load_dword v129, v[130:131], off nt
	global_load_dword v146, v[132:133], off nt
	global_load_dword v147, v[134:135], off nt
	global_load_dword v148, v[136:137], off nt
	global_load_dword v149, v[138:139], off nt
	global_load_dword v150, v[140:141], off nt
	global_load_dword v151, v[142:143], off nt
	global_load_dword v152, v[144:145], off nt
	s_add_u32 s8, s8, 0x20000
	s_addc_u32 s9, s9, 0
	v_add_u32_e32 v130, 0xc40, v6
	s_cmp_lg_u32 s8, 0x80000
	s_waitcnt vmcnt(14)
	ds_write2_b32 v6, v69, v86 offset1:66
	s_waitcnt vmcnt(12)
	ds_write2_b32 v6, v87, v88 offset0:132 offset1:198
	s_waitcnt vmcnt(10)
	ds_write2_b32 v70, v89, v90 offset0:8 offset1:74
	s_waitcnt vmcnt(8)
	ds_write2_b32 v70, v91, v92 offset0:140 offset1:206
	v_add_u32_e32 v6, 0x840, v6
	s_waitcnt vmcnt(6)
	ds_write2_b32 v6, v129, v146 offset1:66
	s_waitcnt vmcnt(4)
	ds_write2_b32 v6, v147, v148 offset0:132 offset1:198
	s_waitcnt vmcnt(2)
	ds_write2_b32 v130, v149, v150 offset0:8 offset1:74
	s_waitcnt vmcnt(0)
	ds_write2_b32 v130, v151, v152 offset0:140 offset1:206
	v_add_u32_e32 v6, 0x840, v6
	s_cbranch_scc1 .LBB0_56
	s_add_i32 s6, s27, 0xffffda00
	s_waitcnt lgkmcnt(0)
	ds_read2_b32 v[96:97], v47 offset1:33
	ds_read2_b32 v[98:99], v47 offset0:66 offset1:99
	ds_read2_b32 v[100:101], v47 offset0:132 offset1:165
	ds_read2_b32 v[102:103], v47 offset0:198 offset1:231
	ds_read2_b32 v[104:105], v47 offset0:8 offset1:41
	ds_read2_b32 v[106:107], v47 offset0:74 offset1:107
	ds_read2_b32 v[108:109], v47 offset0:140 offset1:173
	ds_read2_b32 v[110:111], v47 offset0:206 offset1:239
	ds_read2_b32 v[112:113], v47 offset0:16 offset1:49
	ds_read2_b32 v[114:115], v47 offset0:82 offset1:115
	ds_read2_b32 v[116:117], v47 offset0:148 offset1:181
	ds_read2_b32 v[118:119], v47 offset0:214 offset1:247
	ds_read2_b32 v[120:121], v47 offset0:24 offset1:57
	ds_read2_b32 v[122:123], v47 offset0:90 offset1:123
	ds_read2_b32 v[124:125], v47 offset0:156 offset1:189
	ds_read2_b32 v[126:127], v47 offset0:222 offset1:255
	s_and_b32 s8, s6, 0x1fc0
	s_lshl_b32 s6, s6, 5
	s_nop 0
	s_and_b32 s9, s6, 0x7e0
	s_waitcnt lgkmcnt(0)
	v_cvt_pk_bf16_f32 v0, v96, v97
	s_nop 0
	s_lshl_b32 s6, s8, 1
	v_or_b32_e32 v6, s9, v46
	s_waitcnt lgkmcnt(0)
	v_cvt_pk_bf16_f32 v1, v98, v99
	s_nop 0
	v_lshl_add_u64 v[36:37], v[14:15], 0, s[6:7]
	v_lshlrev_b32_e32 v6, 11, v6
	s_waitcnt lgkmcnt(0)
	v_cvt_pk_bf16_f32 v2, v100, v101
	s_nop 0
	s_waitcnt lgkmcnt(0)
	v_cvt_pk_bf16_f32 v3, v102, v103
	v_lshl_add_u64 v[38:39], v[36:37], 0, v[6:7]
	s_nop 0
	global_store_dwordx4 v[38:39], v[0:3], off nt
	v_or_b32_e32 v6, s9, v48
	v_lshlrev_b32_e32 v6, 11, v6
	s_waitcnt lgkmcnt(0)
	v_cvt_pk_bf16_f32 v0, v104, v105
	s_nop 0
	s_waitcnt lgkmcnt(0)
	v_cvt_pk_bf16_f32 v1, v106, v107
	s_nop 0
	s_waitcnt lgkmcnt(0)
	v_cvt_pk_bf16_f32 v2, v108, v109
	s_nop 0
	s_waitcnt lgkmcnt(0)
	v_cvt_pk_bf16_f32 v3, v110, v111
	v_lshl_add_u64 v[38:39], v[36:37], 0, v[6:7]
	s_nop 0
	global_store_dwordx4 v[38:39], v[0:3], off nt
	v_or_b32_e32 v6, s9, v49
	v_lshlrev_b32_e32 v6, 11, v6
	s_waitcnt lgkmcnt(0)
	v_cvt_pk_bf16_f32 v0, v112, v113
	s_nop 0
	s_waitcnt lgkmcnt(0)
	v_cvt_pk_bf16_f32 v1, v114, v115
	s_nop 0
	s_waitcnt lgkmcnt(0)
	v_cvt_pk_bf16_f32 v2, v116, v117
	s_nop 0
	s_waitcnt lgkmcnt(0)
	v_cvt_pk_bf16_f32 v3, v118, v119
	v_lshl_add_u64 v[38:39], v[36:37], 0, v[6:7]
	s_nop 0
	global_store_dwordx4 v[38:39], v[0:3], off nt
	s_waitcnt lgkmcnt(0)
	s_nop 0
	v_cvt_pk_bf16_f32 v0, v120, v121
	s_nop 0
	s_waitcnt lgkmcnt(0)
	v_cvt_pk_bf16_f32 v1, v122, v123
	s_nop 0
	s_waitcnt lgkmcnt(0)
	v_cvt_pk_bf16_f32 v2, v124, v125
	v_or_b32_e32 v3, s9, v50
	s_nop 0
	v_lshlrev_b32_e32 v6, 11, v3
	s_waitcnt lgkmcnt(0)
	v_cvt_pk_bf16_f32 v3, v126, v127
	v_lshl_add_u64 v[34:35], v[36:37], 0, v[6:7]
	global_store_dwordx4 v[34:35], v[0:3], off nt
	s_waitcnt lgkmcnt(0)

; __device__ __forceinline__ unsigned cvt_pk_bf16(float lo, float hi) { unsigned r; asm volatile("v_cvt_pk_bf16_f32 %0, %1, %2" : "=v"(r) : "v"(lo), "v"(hi)); return r; }
; template <int MAP>
; __device__ __forceinline__ void transpose_item(const float* __restrict__ W, int K, int N, bf16_t* __restrict__ WT, float* scr, int item, int lane) {
;     ...
;     const int c = lane & 7;
; #pragma unroll
;     for (int j = 0; j < 4; ++j) { const int n = (lane >> 3) + 8 * j; const float* s = scr + (8 * c) * 33 + n;
;         u32x4 o; o.x = cvt_pk_bf16(s[0 * 33], s[1 * 33]); o.y = cvt_pk_bf16(s[2 * 33], s[3 * 33]); o.z = cvt_pk_bf16(s[4 * 33], s[5 * 33]); o.w = cvt_pk_bf16(s[6 * 33], s[7 * 33]);
;         if (MAP == 1) *(u32x4*)(WT + (size_t)row_map<MAP>(n0 + n) * K + k0 + 8 * c) = o;
;         else __builtin_nontemporal_store(o, (u32x4*)(WT + (size_t)row_map<MAP>(n0 + n) * K + k0 + 8 * c)); }
.LBB0_61:
	v_lshl_add_u64 v[70:71], v[44:45], 0, s[8:9]
	v_lshl_add_u64 v[72:73], v[42:43], 0, s[8:9]
	v_lshl_add_u64 v[74:75], v[40:41], 0, s[8:9]
	v_lshl_add_u64 v[76:77], v[38:39], 0, s[8:9]
	v_lshl_add_u64 v[78:79], v[36:37], 0, s[8:9]
	v_lshl_add_u64 v[80:81], v[34:35], 0, s[8:9]
	v_lshl_add_u64 v[82:83], v[2:3], 0, s[8:9]
	v_lshl_add_u64 v[84:85], v[0:1], 0, s[8:9]
	global_load_dword v69, v[70:71], off nt
	global_load_dword v86, v[72:73], off nt
	global_load_dword v87, v[74:75], off nt
	global_load_dword v88, v[76:77], off nt
	global_load_dword v89, v[78:79], off nt
	global_load_dword v90, v[80:81], off nt
	global_load_dword v91, v[82:83], off nt
	global_load_dword v92, v[84:85], off nt
	s_add_u32 s8, s8, 0x20000
	s_addc_u32 s9, s9, 0
	v_add_u32_e32 v70, 0x400, v6
	s_cmp_lg_u32 s8, 0x80000
	v_lshl_add_u64 v[130:131], v[44:45], 0, s[8:9]
	v_lshl_add_u64 v[132:133], v[42:43], 0, s[8:9]
	v_lshl_add_u64 v[134:135], v[40:41], 0, s[8:9]
	v_lshl_add_u64 v[136:137], v[38:39], 0, s[8:9]
	v_lshl_add_u64 v[138:139], v[36:37], 0, s[8:9]
	v_lshl_add_u64 v[140:141], v[34:35], 0, s[8:9]
	v_lshl_add_u64 v[142:143], v[2:3], 0, s[8:9]
	v_lshl_add_u64 v[144:145], v[0:1], 0, s[8:9]
	global_load_dword v129, v[130:131], off nt
	global_load_dword v146, v[132:133], off nt
	global_load_dword v147, v[134:135], off nt
	global_load_dword v148, v[136:137], off nt
	global_load_dword v149, v[138:139], off nt
	global_load_dword v150, v[140:141], off nt
	global_load_dword v151, v[142:143], off nt
	global_load_dword v152, v[144:145], off nt
	s_add_u32 s8, s8, 0x20000
	s_addc_u32 s9, s9, 0
	v_add_u32_e32 v130, 0xc40, v6
	s_cmp_lg_u32 s8, 0x80000
	s_waitcnt vmcnt(14)
	ds_write2_b32 v6, v69, v86 offset1:66
	s_waitcnt vmcnt(12)
	ds_write2_b32 v6, v87, v88 offset0:132 offset1:198
	s_waitcnt vmcnt(10)
	ds_write2_b32 v70, v89, v90 offset0:8 offset1:74
	s_waitcnt vmcnt(8)
	ds_write2_b32 v70, v91, v92 offset0:140 offset1:206
	v_add_u32_e32 v6, 0x840, v6
	s_waitcnt vmcnt(6)
	ds_write2_b32 v6, v129, v146 offset1:66
	s_waitcnt vmcnt(4)
	ds_write2_b32 v6, v147, v148 offset0:132 offset1:198
	s_waitcnt vmcnt(2)
	ds_write2_b32 v130, v149, v150 offset0:8 offset1:74
	s_waitcnt vmcnt(0)
	ds_write2_b32 v130, v151, v152 offset0:140 offset1:206
	v_add_u32_e32 v6, 0x840, v6
	s_cbranch_scc1 .LBB0_61
	s_add_i32 s6, s27, 0xffffde00
	s_waitcnt lgkmcnt(0)
	ds_read2_b32 v[96:97], v47 offset1:33
	ds_read2_b32 v[98:99], v47 offset0:66 offset1:99
	ds_read2_b32 v[100:101], v47 offset0:132 offset1:165
	ds_read2_b32 v[102:103], v47 offset0:198 offset1:231
	ds_read2_b32 v[104:105], v47 offset0:8 offset1:41
	ds_read2_b32 v[106:107], v47 offset0:74 offset1:107
	ds_read2_b32 v[108:109], v47 offset0:140 offset1:173
	ds_read2_b32 v[110:111], v47 offset0:206 offset1:239
	ds_read2_b32 v[112:113], v47 offset0:16 offset1:49
	ds_read2_b32 v[114:115], v47 offset0:82 offset1:115
	ds_read2_b32 v[116:117], v47 offset0:148 offset1:181
	ds_read2_b32 v[118:119], v47 offset0:214 offset1:247
	ds_read2_b32 v[120:121], v47 offset0:24 offset1:57
	ds_read2_b32 v[122:123], v47 offset0:90 offset1:123
	ds_read2_b32 v[124:125], v47 offset0:156 offset1:189
	ds_read2_b32 v[126:127], v47 offset0:222 offset1:255
	s_and_b32 s8, s6, 0x1fc0
	s_lshl_b32 s6, s6, 5
	s_nop 0
	s_and_b32 s9, s6, 0x7e0
	s_waitcnt lgkmcnt(0)
	v_cvt_pk_bf16_f32 v0, v96, v97
	s_nop 0
	s_lshl_b32 s6, s8, 1
	v_or_b32_e32 v6, s9, v46
	s_waitcnt lgkmcnt(0)
	v_cvt_pk_bf16_f32 v1, v98, v99
	s_nop 0
	v_lshl_add_u64 v[36:37], v[16:17], 0, s[6:7]
	v_lshlrev_b32_e32 v6, 11, v6
	s_waitcnt lgkmcnt(0)
	v_cvt_pk_bf16_f32 v2, v100, v101
	s_nop 0
	s_waitcnt lgkmcnt(0)
	v_cvt_pk_bf16_f32 v3, v102, v103
	v_lshl_add_u64 v[38:39], v[36:37], 0, v[6:7]
	s_nop 0
	global_store_dwordx4 v[38:39], v[0:3], off nt
	v_or_b32_e32 v6, s9, v48
	v_lshlrev_b32_e32 v6, 11, v6
	s_waitcnt lgkmcnt(0)
	v_cvt_pk_bf16_f32 v0, v104, v105
	s_nop 0
	s_waitcnt lgkmcnt(0)
	v_cvt_pk_bf16_f32 v1, v106, v107
	s_nop 0
	s_waitcnt lgkmcnt(0)
	v_cvt_pk_bf16_f32 v2, v108, v109
	s_nop 0
	s_waitcnt lgkmcnt(0)
	v_cvt_pk_bf16_f32 v3, v110, v111
	v_lshl_add_u64 v[38:39], v[36:37], 0, v[6:7]
	s_nop 0
	global_store_dwordx4 v[38:39], v[0:3], off nt
	v_or_b32_e32 v6, s9, v49
	v_lshlrev_b32_e32 v6, 11, v6
	s_waitcnt lgkmcnt(0)
	v_cvt_pk_bf16_f32 v0, v112, v113
	s_nop 0
	s_waitcnt lgkmcnt(0)
	v_cvt_pk_bf16_f32 v1, v114, v115
	s_nop 0
	s_waitcnt lgkmcnt(0)
	v_cvt_pk_bf16_f32 v2, v116, v117
	s_nop 0
	s_waitcnt lgkmcnt(0)
	v_cvt_pk_bf16_f32 v3, v118, v119
	v_lshl_add_u64 v[38:39], v[36:37], 0, v[6:7]
	s_nop 0
	global_store_dwordx4 v[38:39], v[0:3], off nt
	s_waitcnt lgkmcnt(0)
	s_nop 0
	v_cvt_pk_bf16_f32 v0, v120, v121
	s_nop 0
	s_waitcnt lgkmcnt(0)
	v_cvt_pk_bf16_f32 v1, v122, v123
	s_nop 0
	s_waitcnt lgkmcnt(0)
	v_cvt_pk_bf16_f32 v2, v124, v125
	v_or_b32_e32 v3, s9, v50
	s_nop 0
	v_lshlrev_b32_e32 v6, 11, v3
	s_waitcnt lgkmcnt(0)
	v_cvt_pk_bf16_f32 v3, v126, v127
	v_lshl_add_u64 v[34:35], v[36:37], 0, v[6:7]
	global_store_dwordx4 v[34:35], v[0:3], off nt
	s_waitcnt lgkmcnt(0)

; __device__ __forceinline__ unsigned cvt_pk_bf16(float lo, float hi) { unsigned r; asm volatile("v_cvt_pk_bf16_f32 %0, %1, %2" : "=v"(r) : "v"(lo), "v"(hi)); return r; }
; template <int MAP>
; __device__ __forceinline__ void transpose_item(const float* __restrict__ W, int K, int N, bf16_t* __restrict__ WT, float* scr, int item, int lane) {
;     ...
;     const int c = lane & 7;
; #pragma unroll
;     for (int j = 0; j < 4; ++j) { const int n = (lane >> 3) + 8 * j; const float* s = scr + (8 * c) * 33 + n;
;         u32x4 o; o.x = cvt_pk_bf16(s[0 * 33], s[1 * 33]); o.y = cvt_pk_bf16(s[2 * 33], s[3 * 33]); o.z = cvt_pk_bf16(s[4 * 33], s[5 * 33]); o.w = cvt_pk_bf16(s[6 * 33], s[7 * 33]);
;         if (MAP == 1) *(u32x4*)(WT + (size_t)row_map<MAP>(n0 + n) * K + k0 + 8 * c) = o;
;         else __builtin_nontemporal_store(o, (u32x4*)(WT + (size_t)row_map<MAP>(n0 + n) * K + k0 + 8 * c)); }
.LBB0_241:
	v_lshl_add_u64 v[70:71], v[44:45], 0, s[0:1]
	v_lshl_add_u64 v[72:73], v[42:43], 0, s[0:1]
	v_lshl_add_u64 v[74:75], v[40:41], 0, s[0:1]
	v_lshl_add_u64 v[76:77], v[38:39], 0, s[0:1]
	v_lshl_add_u64 v[78:79], v[36:37], 0, s[0:1]
	v_lshl_add_u64 v[80:81], v[34:35], 0, s[0:1]
	v_lshl_add_u64 v[82:83], v[4:5], 0, s[0:1]
	v_lshl_add_u64 v[84:85], v[2:3], 0, s[0:1]
	global_load_dword v69, v[70:71], off nt
	s_nop 0
	global_load_dword v70, v[72:73], off nt
	global_load_dword v71, v[74:75], off nt
	s_nop 0
	global_load_dword v72, v[76:77], off nt
	global_load_dword v73, v[78:79], off nt
	global_load_dword v74, v[80:81], off nt
	global_load_dword v75, v[82:83], off nt
	s_nop 0
	global_load_dword v76, v[84:85], off nt
	s_add_u32 s0, s0, 0x20000
	s_addc_u32 s1, s1, 0
	v_add_u32_e32 v77, 0x400, v0
	s_cmp_lg_u32 s0, 0x80000
	v_lshl_add_u64 v[130:131], v[44:45], 0, s[0:1]
	v_lshl_add_u64 v[132:133], v[42:43], 0, s[0:1]
	v_lshl_add_u64 v[134:135], v[40:41], 0, s[0:1]
	v_lshl_add_u64 v[136:137], v[38:39], 0, s[0:1]
	v_lshl_add_u64 v[138:139], v[36:37], 0, s[0:1]
	v_lshl_add_u64 v[140:141], v[34:35], 0, s[0:1]
	v_lshl_add_u64 v[142:143], v[4:5], 0, s[0:1]
	v_lshl_add_u64 v[144:145], v[2:3], 0, s[0:1]
	global_load_dword v129, v[130:131], off nt
	s_nop 0
	global_load_dword v130, v[132:133], off nt
	global_load_dword v131, v[134:135], off nt
	s_nop 0
	global_load_dword v132, v[136:137], off nt
	global_load_dword v133, v[138:139], off nt
	global_load_dword v134, v[140:141], off nt
	global_load_dword v135, v[142:143], off nt
	s_nop 0
	global_load_dword v136, v[144:145], off nt
	s_add_u32 s0, s0, 0x20000
	s_addc_u32 s1, s1, 0
	v_add_u32_e32 v137, 0xc40, v0
	s_cmp_lg_u32 s0, 0x80000
	s_waitcnt vmcnt(14)
	ds_write2_b32 v0, v69, v70 offset1:66
	s_waitcnt vmcnt(12)
	ds_write2_b32 v0, v71, v72 offset0:132 offset1:198
	s_waitcnt vmcnt(10)
	ds_write2_b32 v77, v73, v74 offset0:8 offset1:74
	s_waitcnt vmcnt(8)
	ds_write2_b32 v77, v75, v76 offset0:140 offset1:206
	v_add_u32_e32 v0, 0x840, v0
	s_waitcnt vmcnt(6)
	ds_write2_b32 v0, v129, v130 offset1:66
	s_waitcnt vmcnt(4)
	ds_write2_b32 v0, v131, v132 offset0:132 offset1:198
	s_waitcnt vmcnt(2)
	ds_write2_b32 v137, v133, v134 offset0:8 offset1:74
	s_waitcnt vmcnt(0)
	ds_write2_b32 v137, v135, v136 offset0:140 offset1:206
	v_add_u32_e32 v0, 0x840, v0
	s_cbranch_scc1 .LBB0_241
	s_add_i32 s0, s18, 0xffffa200
	s_and_b32 s1, s0, 0x1fc0
	s_lshl_b32 s0, s0, 5
	s_waitcnt lgkmcnt(0)
	ds_read2_b32 v[96:97], v47 offset1:33
	ds_read2_b32 v[98:99], v47 offset0:66 offset1:99
	ds_read2_b32 v[100:101], v47 offset0:132 offset1:165
	ds_read2_b32 v[102:103], v47 offset0:198 offset1:231
	ds_read2_b32 v[104:105], v47 offset0:8 offset1:41
	ds_read2_b32 v[106:107], v47 offset0:74 offset1:107
	ds_read2_b32 v[108:109], v47 offset0:140 offset1:173
	ds_read2_b32 v[110:111], v47 offset0:206 offset1:239
	ds_read2_b32 v[112:113], v47 offset0:16 offset1:49
	ds_read2_b32 v[114:115], v47 offset0:82 offset1:115
	ds_read2_b32 v[116:117], v47 offset0:148 offset1:181
	ds_read2_b32 v[118:119], v47 offset0:214 offset1:247
	ds_read2_b32 v[120:121], v47 offset0:24 offset1:57
	ds_read2_b32 v[122:123], v47 offset0:90 offset1:123
	ds_read2_b32 v[124:125], v47 offset0:156 offset1:189
	ds_read2_b32 v[126:127], v47 offset0:222 offset1:255
	s_and_b32 s0, s0, 0x7e0
	s_nop 0
	v_or_b32_e32 v0, s0, v46
	s_waitcnt lgkmcnt(0)
	v_cvt_pk_bf16_f32 v2, v96, v97
	s_nop 0
	s_lshl_b32 s60, s1, 1
	v_mul_u32_u24_e32 v0, 0x1600, v0
	s_waitcnt lgkmcnt(0)
	v_cvt_pk_bf16_f32 v3, v98, v99
	s_nop 0
	v_lshl_add_u64 v[36:37], v[8:9], 0, s[60:61]
	v_lshlrev_b32_e32 v0, 1, v0
	s_waitcnt lgkmcnt(0)
	v_cvt_pk_bf16_f32 v4, v100, v101
	s_nop 0
	s_waitcnt lgkmcnt(0)
	v_cvt_pk_bf16_f32 v5, v102, v103
	v_lshl_add_u64 v[38:39], v[36:37], 0, v[0:1]
	v_or_b32_e32 v0, s0, v48
	s_nop 0
	global_store_dwordx4 v[38:39], v[2:5], off nt
	v_mul_u32_u24_e32 v0, 0x1600, v0
	v_lshlrev_b32_e32 v0, 1, v0
	s_waitcnt lgkmcnt(0)
	v_cvt_pk_bf16_f32 v2, v104, v105
	s_nop 0
	s_waitcnt lgkmcnt(0)
	v_cvt_pk_bf16_f32 v3, v106, v107
	s_nop 0
	s_waitcnt lgkmcnt(0)
	v_cvt_pk_bf16_f32 v4, v108, v109
	s_nop 0
	s_waitcnt lgkmcnt(0)
	v_cvt_pk_bf16_f32 v5, v110, v111
	v_lshl_add_u64 v[38:39], v[36:37], 0, v[0:1]
	v_or_b32_e32 v0, s0, v49
	s_nop 0
	global_store_dwordx4 v[38:39], v[2:5], off nt
	v_mul_u32_u24_e32 v0, 0x1600, v0
	v_lshlrev_b32_e32 v0, 1, v0
	s_waitcnt lgkmcnt(0)
	v_cvt_pk_bf16_f32 v2, v112, v113
	s_nop 0
	s_waitcnt lgkmcnt(0)
	v_cvt_pk_bf16_f32 v3, v114, v115
	s_nop 0
	s_waitcnt lgkmcnt(0)
	v_cvt_pk_bf16_f32 v4, v116, v117
	s_nop 0
	s_waitcnt lgkmcnt(0)
	v_cvt_pk_bf16_f32 v5, v118, v119
	v_lshl_add_u64 v[38:39], v[36:37], 0, v[0:1]
	s_nop 0
	global_store_dwordx4 v[38:39], v[2:5], off nt
	v_or_b32_e32 v0, s0, v50
	v_mul_u32_u24_e32 v0, 0x1600, v0
	s_waitcnt lgkmcnt(0)
	v_cvt_pk_bf16_f32 v2, v120, v121
	s_nop 0
	s_waitcnt lgkmcnt(0)
	v_cvt_pk_bf16_f32 v3, v122, v123
	s_nop 0
	s_waitcnt lgkmcnt(0)
	v_cvt_pk_bf16_f32 v4, v124, v125
	s_nop 0
	v_lshlrev_b32_e32 v0, 1, v0
	s_waitcnt lgkmcnt(0)
	v_cvt_pk_bf16_f32 v5, v126, v127
	v_lshl_add_u64 v[34:35], v[36:37], 0, v[0:1]
	global_store_dwordx4 v[34:35], v[2:5], off nt
	s_waitcnt lgkmcnt(0)
	s_mov_b64 s[0:1], 0

; __device__ __forceinline__ unsigned cvt_pk_bf16(float lo, float hi) { unsigned r; asm volatile("v_cvt_pk_bf16_f32 %0, %1, %2" : "=v"(r) : "v"(lo), "v"(hi)); return r; }
; template <int MAP>
; __device__ __forceinline__ int row_map(int n) {
;     ...
;     if (MAP == 2) { const int c = n < FF ? n : n - FF; return 256 * (c >> 7) + (c & 127) + (n < FF ? 0 : 128); }
; template <int MAP>
; __device__ __forceinline__ void transpose_item(const float* __restrict__ W, int K, int N, bf16_t* __restrict__ WT, float* scr, int item, int lane) {
;     ...
;     const int c = lane & 7;
; #pragma unroll
;     for (int j = 0; j < 4; ++j) { const int n = (lane >> 3) + 8 * j; const float* s = scr + (8 * c) * 33 + n;
;         u32x4 o; o.x = cvt_pk_bf16(s[0 * 33], s[1 * 33]); o.y = cvt_pk_bf16(s[2 * 33], s[3 * 33]); o.z = cvt_pk_bf16(s[4 * 33], s[5 * 33]); o.w = cvt_pk_bf16(s[6 * 33], s[7 * 33]);
;         if (MAP == 1) *(u32x4*)(WT + (size_t)row_map<MAP>(n0 + n) * K + k0 + 8 * c) = o;
;         else __builtin_nontemporal_store(o, (u32x4*)(WT + (size_t)row_map<MAP>(n0 + n) * K + k0 + 8 * c)); }
.LBB0_245:
	v_lshl_add_u64 v[44:45], v[38:39], 0, s[12:13]
	v_add_co_u32_e32 v78, vcc, 0x5816000, v44
	v_lshl_add_u64 v[42:43], v[40:41], 0, s[12:13]
	v_lshl_add_u64 v[70:71], v[36:37], 0, s[12:13]
	v_lshl_add_u64 v[72:73], v[34:35], 0, s[12:13]
	s_mov_b64 s[0:1], vcc
	v_lshl_add_u64 v[74:75], v[4:5], 0, s[12:13]
	v_lshl_add_u64 v[76:77], v[2:3], 0, s[12:13]
	global_load_dword v69, v[42:43], off nt
	s_nop 0
	global_load_dword v70, v[70:71], off nt
	s_nop 0
	global_load_dword v71, v[72:73], off nt
	s_nop 0
	global_load_dword v72, v[74:75], off nt
	global_load_dword v73, v[76:77], off nt
	v_add_co_u32_e32 v42, vcc, 0x582c000, v44
	v_addc_co_u32_e64 v79, s[0:1], 0, v45, s[0:1]
	s_mov_b64 s[0:1], vcc
	v_add_co_u32_e32 v44, vcc, 0x5842000, v44
	v_addc_co_u32_e64 v43, s[0:1], 0, v45, s[0:1]
	global_load_dword v74, v[78:79], off nt
	v_addc_co_u32_e32 v45, vcc, 0, v45, vcc
	global_load_dword v42, v[42:43], off nt
	s_nop 0
	global_load_dword v43, v[44:45], off nt
	s_add_u32 s12, s12, 0xb0000
	v_add_u32_e32 v44, 0x400, v0
	s_addc_u32 s13, s13, 0
	s_cmp_lg_u32 s12, 0x2c0000
	v_lshl_add_u64 v[104:105], v[38:39], 0, s[12:13]
	v_add_co_u32_e32 v138, vcc, 0x5816000, v104
	v_lshl_add_u64 v[102:103], v[40:41], 0, s[12:13]
	v_lshl_add_u64 v[130:131], v[36:37], 0, s[12:13]
	v_lshl_add_u64 v[132:133], v[34:35], 0, s[12:13]
	s_mov_b64 s[0:1], vcc
	v_lshl_add_u64 v[134:135], v[4:5], 0, s[12:13]
	v_lshl_add_u64 v[136:137], v[2:3], 0, s[12:13]
	global_load_dword v129, v[102:103], off nt
	s_nop 0
	global_load_dword v130, v[130:131], off nt
	s_nop 0
	global_load_dword v131, v[132:133], off nt
	s_nop 0
	global_load_dword v132, v[134:135], off nt
	global_load_dword v133, v[136:137], off nt
	v_add_co_u32_e32 v102, vcc, 0x582c000, v104
	v_addc_co_u32_e64 v139, s[0:1], 0, v105, s[0:1]
	s_mov_b64 s[0:1], vcc
	v_add_co_u32_e32 v104, vcc, 0x5842000, v104
	v_addc_co_u32_e64 v103, s[0:1], 0, v105, s[0:1]
	global_load_dword v134, v[138:139], off nt
	v_addc_co_u32_e32 v105, vcc, 0, v105, vcc
	global_load_dword v102, v[102:103], off nt
	s_nop 0
	global_load_dword v103, v[104:105], off nt
	s_add_u32 s12, s12, 0xb0000
	v_add_u32_e32 v104, 0xc40, v0
	s_addc_u32 s13, s13, 0
	s_cmp_lg_u32 s12, 0x2c0000
	s_waitcnt vmcnt(13)
	ds_write2_b32 v44, v70, v71 offset0:8 offset1:74
	s_waitcnt vmcnt(11)
	ds_write2_b32 v44, v72, v73 offset0:140 offset1:206
	s_waitcnt vmcnt(10)
	ds_write2_b32 v0, v69, v74 offset1:66
	s_waitcnt vmcnt(8)
	ds_write2_b32 v0, v42, v43 offset0:132 offset1:198
	v_add_u32_e32 v0, 0x840, v0
	s_waitcnt vmcnt(5)
	ds_write2_b32 v104, v130, v131 offset0:8 offset1:74
	s_waitcnt vmcnt(3)
	ds_write2_b32 v104, v132, v133 offset0:140 offset1:206
	s_waitcnt vmcnt(2)
	ds_write2_b32 v0, v129, v134 offset1:66
	s_waitcnt vmcnt(0)
	ds_write2_b32 v0, v102, v103 offset0:132 offset1:198
	v_add_u32_e32 v0, 0x840, v0
	s_cbranch_scc1 .LBB0_245
	s_and_b32 s0, 0xffff, s15
	s_waitcnt lgkmcnt(0)
	ds_read2_b32 v[96:97], v47 offset1:33
	ds_read2_b32 v[98:99], v47 offset0:66 offset1:99
	ds_read2_b32 v[100:101], v47 offset0:132 offset1:165
	ds_read2_b32 v[102:103], v47 offset0:198 offset1:231
	ds_read2_b32 v[104:105], v47 offset0:8 offset1:41
	ds_read2_b32 v[106:107], v47 offset0:74 offset1:107
	ds_read2_b32 v[108:109], v47 offset0:140 offset1:173
	ds_read2_b32 v[110:111], v47 offset0:206 offset1:239
	ds_read2_b32 v[112:113], v47 offset0:16 offset1:49
	ds_read2_b32 v[114:115], v47 offset0:82 offset1:115
	ds_read2_b32 v[116:117], v47 offset0:148 offset1:181
	ds_read2_b32 v[118:119], v47 offset0:214 offset1:247
	ds_read2_b32 v[120:121], v47 offset0:24 offset1:57
	ds_read2_b32 v[122:123], v47 offset0:90 offset1:123
	ds_read2_b32 v[124:125], v47 offset0:156 offset1:189
	ds_read2_b32 v[126:127], v47 offset0:222 offset1:255
	s_and_b32 s12, 0xffff, s16
	s_and_b32 s1, 0xffff, s14
	s_lshl_b32 s60, s0, 1
	s_nop 0
	v_or_b32_e32 v0, s12, v46
	s_cmpk_lt_u32 s1, 0xb0
	s_waitcnt lgkmcnt(0)
	v_cvt_pk_bf16_f32 v2, v96, v97
	s_nop 0
	v_add_u32_e32 v38, 0xffffea00, v0
	s_cselect_b64 vcc, -1, 0
	s_waitcnt lgkmcnt(0)
	v_cvt_pk_bf16_f32 v3, v98, v99
	s_nop 0
	v_cndmask_b32_e32 v0, v38, v0, vcc
	s_waitcnt lgkmcnt(0)
	v_cvt_pk_bf16_f32 v4, v100, v101
	v_lshlrev_b32_e32 v5, 1, v0
	s_and_b64 s[0:1], vcc, exec
	s_nop 0
	v_and_b32_e32 v0, 0x67, v0
	v_and_b32_e32 v38, 0xffffff00, v5
	s_cselect_b32 s0, 0, 0x80
	s_waitcnt lgkmcnt(0)
	v_cvt_pk_bf16_f32 v5, v102, v103
	v_or3_b32 v36, v0, v38, s0
	v_ashrrev_i32_e32 v37, 31, v36
	v_lshl_add_u64 v[34:35], v[10:11], 0, s[60:61]
	v_lshlrev_b64 v[36:37], 12, v[36:37]
	v_lshl_add_u64 v[36:37], v[34:35], 0, v[36:37]
	s_nop 0
	global_store_dwordx4 v[36:37], v[2:5], off nt
	v_or_b32_e32 v0, s12, v48
	s_waitcnt lgkmcnt(0)
	v_cvt_pk_bf16_f32 v2, v104, v105
	s_nop 0
	s_waitcnt lgkmcnt(0)
	v_cvt_pk_bf16_f32 v3, v106, v107
	s_nop 0
	s_waitcnt lgkmcnt(0)
	v_cvt_pk_bf16_f32 v4, v108, v109
	v_add_u32_e32 v5, 0xffffea00, v0
	v_cndmask_b32_e32 v0, v5, v0, vcc
	v_lshlrev_b32_e32 v5, 1, v0
	s_nop 0
	v_and_b32_e32 v38, 0xffffff00, v5
	v_and_b32_e32 v0, 0x6f, v0
	s_waitcnt lgkmcnt(0)
	v_cvt_pk_bf16_f32 v5, v110, v111
	v_or3_b32 v36, v0, v38, s0
	v_ashrrev_i32_e32 v37, 31, v36
	v_lshlrev_b64 v[36:37], 12, v[36:37]
	s_nop 0
	v_lshl_add_u64 v[36:37], v[34:35], 0, v[36:37]
	v_or_b32_e32 v0, s12, v49
	global_store_dwordx4 v[36:37], v[2:5], off nt
	s_waitcnt lgkmcnt(0)
	s_nop 0
	v_cvt_pk_bf16_f32 v2, v112, v113
	s_nop 0
	v_add_u32_e32 v38, 0xffffea00, v0
	s_waitcnt lgkmcnt(0)
	v_cvt_pk_bf16_f32 v3, v114, v115
	s_nop 0
	v_cndmask_b32_e32 v0, v38, v0, vcc
	s_waitcnt lgkmcnt(0)
	v_cvt_pk_bf16_f32 v4, v116, v117
	v_lshlrev_b32_e32 v5, 1, v0
	s_nop 0
	v_and_b32_e32 v0, 0x77, v0
	v_and_b32_e32 v38, 0xffffff00, v5
	s_waitcnt lgkmcnt(0)
	v_cvt_pk_bf16_f32 v5, v118, v119
	v_or3_b32 v36, v0, v38, s0
	v_ashrrev_i32_e32 v37, 31, v36
	v_lshlrev_b64 v[36:37], 12, v[36:37]
	v_lshl_add_u64 v[36:37], v[34:35], 0, v[36:37]
	v_or_b32_e32 v0, s12, v50
	s_nop 0
	global_store_dwordx4 v[36:37], v[2:5], off nt
	v_add_u32_e32 v36, 0xffffea00, v0
	v_cndmask_b32_e32 v0, v36, v0, vcc
	s_waitcnt lgkmcnt(0)
	v_cvt_pk_bf16_f32 v2, v120, v121
	s_nop 0
	s_waitcnt lgkmcnt(0)
	v_cvt_pk_bf16_f32 v3, v122, v123
	s_nop 0
	s_waitcnt lgkmcnt(0)
	v_cvt_pk_bf16_f32 v4, v124, v125
	v_lshlrev_b32_e32 v5, 1, v0
	v_and_b32_e32 v0, 0x7f, v0
	v_and_b32_e32 v5, 0xffffff00, v5
	v_or3_b32 v38, v0, v5, s0
	s_nop 0
	v_ashrrev_i32_e32 v39, 31, v38
	s_waitcnt lgkmcnt(0)
	v_cvt_pk_bf16_f32 v5, v126, v127
	v_lshlrev_b64 v[36:37], 12, v[38:39]
	v_lshl_add_u64 v[34:35], v[34:35], 0, v[36:37]
	global_store_dwordx4 v[34:35], v[2:5], off nt
	s_waitcnt lgkmcnt(0)

; __device__ __forceinline__ unsigned cvt_pk_bf16(float lo, float hi) { unsigned r; asm volatile("v_cvt_pk_bf16_f32 %0, %1, %2" : "=v"(r) : "v"(lo), "v"(hi)); return r; }
; template <int MAP>
; __device__ __forceinline__ void transpose_item(const float* __restrict__ W, int K, int N, bf16_t* __restrict__ WT, float* scr, int item, int lane) {
;     ...
;     const int c = lane & 7;
; #pragma unroll
;     for (int j = 0; j < 4; ++j) { const int n = (lane >> 3) + 8 * j; const float* s = scr + (8 * c) * 33 + n;
;         u32x4 o; o.x = cvt_pk_bf16(s[0 * 33], s[1 * 33]); o.y = cvt_pk_bf16(s[2 * 33], s[3 * 33]); o.z = cvt_pk_bf16(s[4 * 33], s[5 * 33]); o.w = cvt_pk_bf16(s[6 * 33], s[7 * 33]);
;         if (MAP == 1) *(u32x4*)(WT + (size_t)row_map<MAP>(n0 + n) * K + k0 + 8 * c) = o;
;         else __builtin_nontemporal_store(o, (u32x4*)(WT + (size_t)row_map<MAP>(n0 + n) * K + k0 + 8 * c)); }
.LBB0_250:
	v_lshl_add_u64 v[70:71], v[44:45], 0, s[0:1]
	v_lshl_add_u64 v[72:73], v[42:43], 0, s[0:1]
	v_lshl_add_u64 v[74:75], v[40:41], 0, s[0:1]
	v_lshl_add_u64 v[76:77], v[38:39], 0, s[0:1]
	v_lshl_add_u64 v[78:79], v[36:37], 0, s[0:1]
	v_lshl_add_u64 v[80:81], v[34:35], 0, s[0:1]
	v_lshl_add_u64 v[82:83], v[4:5], 0, s[0:1]
	v_lshl_add_u64 v[84:85], v[2:3], 0, s[0:1]
	global_load_dword v69, v[70:71], off nt
	s_nop 0
	global_load_dword v70, v[72:73], off nt
	global_load_dword v71, v[74:75], off nt
	s_nop 0
	global_load_dword v72, v[76:77], off nt
	global_load_dword v73, v[78:79], off nt
	global_load_dword v74, v[80:81], off nt
	global_load_dword v75, v[82:83], off nt
	s_nop 0
	global_load_dword v76, v[84:85], off nt
	s_add_u32 s0, s0, 0x20000
	s_addc_u32 s1, s1, 0
	v_add_u32_e32 v77, 0x400, v0
	s_cmp_lg_u32 s0, 0x80000
	v_lshl_add_u64 v[130:131], v[44:45], 0, s[0:1]
	v_lshl_add_u64 v[132:133], v[42:43], 0, s[0:1]
	v_lshl_add_u64 v[134:135], v[40:41], 0, s[0:1]
	v_lshl_add_u64 v[136:137], v[38:39], 0, s[0:1]
	v_lshl_add_u64 v[138:139], v[36:37], 0, s[0:1]
	v_lshl_add_u64 v[140:141], v[34:35], 0, s[0:1]
	v_lshl_add_u64 v[142:143], v[4:5], 0, s[0:1]
	v_lshl_add_u64 v[144:145], v[2:3], 0, s[0:1]
	global_load_dword v129, v[130:131], off nt
	s_nop 0
	global_load_dword v130, v[132:133], off nt
	global_load_dword v131, v[134:135], off nt
	s_nop 0
	global_load_dword v132, v[136:137], off nt
	global_load_dword v133, v[138:139], off nt
	global_load_dword v134, v[140:141], off nt
	global_load_dword v135, v[142:143], off nt
	s_nop 0
	global_load_dword v136, v[144:145], off nt
	s_add_u32 s0, s0, 0x20000
	s_addc_u32 s1, s1, 0
	v_add_u32_e32 v137, 0xc40, v0
	s_cmp_lg_u32 s0, 0x80000
	s_waitcnt vmcnt(14)
	ds_write2_b32 v0, v69, v70 offset1:66
	s_waitcnt vmcnt(12)
	ds_write2_b32 v0, v71, v72 offset0:132 offset1:198
	s_waitcnt vmcnt(10)
	ds_write2_b32 v77, v73, v74 offset0:8 offset1:74
	s_waitcnt vmcnt(8)
	ds_write2_b32 v77, v75, v76 offset0:140 offset1:206
	v_add_u32_e32 v0, 0x840, v0
	s_waitcnt vmcnt(6)
	ds_write2_b32 v0, v129, v130 offset1:66
	s_waitcnt vmcnt(4)
	ds_write2_b32 v0, v131, v132 offset0:132 offset1:198
	s_waitcnt vmcnt(2)
	ds_write2_b32 v137, v133, v134 offset0:8 offset1:74
	s_waitcnt vmcnt(0)
	ds_write2_b32 v137, v135, v136 offset0:140 offset1:206
	v_add_u32_e32 v0, 0x840, v0
	s_cbranch_scc1 .LBB0_250
	s_add_i32 s0, s18, 0xffffd600
	s_waitcnt lgkmcnt(0)
	ds_read2_b32 v[96:97], v47 offset1:33
	ds_read2_b32 v[98:99], v47 offset0:66 offset1:99
	ds_read2_b32 v[100:101], v47 offset0:132 offset1:165
	ds_read2_b32 v[102:103], v47 offset0:198 offset1:231
	ds_read2_b32 v[104:105], v47 offset0:8 offset1:41
	ds_read2_b32 v[106:107], v47 offset0:74 offset1:107
	ds_read2_b32 v[108:109], v47 offset0:140 offset1:173
	ds_read2_b32 v[110:111], v47 offset0:206 offset1:239
	ds_read2_b32 v[112:113], v47 offset0:16 offset1:49
	ds_read2_b32 v[114:115], v47 offset0:82 offset1:115
	ds_read2_b32 v[116:117], v47 offset0:148 offset1:181
	ds_read2_b32 v[118:119], v47 offset0:214 offset1:247
	ds_read2_b32 v[120:121], v47 offset0:24 offset1:57
	ds_read2_b32 v[122:123], v47 offset0:90 offset1:123
	ds_read2_b32 v[124:125], v47 offset0:156 offset1:189
	ds_read2_b32 v[126:127], v47 offset0:222 offset1:255
	s_and_b32 s1, s0, 0x1fc0
	s_lshl_b32 s0, s0, 5
	s_nop 0
	s_and_b32 s0, s0, 0x7e0
	s_waitcnt lgkmcnt(0)
	v_cvt_pk_bf16_f32 v2, v96, v97
	s_nop 0
	s_lshl_b32 s60, s1, 1
	v_or_b32_e32 v0, s0, v46
	s_waitcnt lgkmcnt(0)
	v_cvt_pk_bf16_f32 v3, v98, v99
	s_nop 0
	v_lshl_add_u64 v[36:37], v[12:13], 0, s[60:61]
	v_lshlrev_b32_e32 v0, 12, v0
	s_waitcnt lgkmcnt(0)
	v_cvt_pk_bf16_f32 v4, v100, v101
	s_nop 0
	s_waitcnt lgkmcnt(0)
	v_cvt_pk_bf16_f32 v5, v102, v103
	v_lshl_add_u64 v[38:39], v[36:37], 0, v[0:1]
	s_nop 0
	global_store_dwordx4 v[38:39], v[2:5], off nt
	v_or_b32_e32 v0, s0, v48
	v_lshlrev_b32_e32 v0, 12, v0
	s_waitcnt lgkmcnt(0)
	v_cvt_pk_bf16_f32 v2, v104, v105
	s_nop 0
	s_waitcnt lgkmcnt(0)
	v_cvt_pk_bf16_f32 v3, v106, v107
	s_nop 0
	s_waitcnt lgkmcnt(0)
	v_cvt_pk_bf16_f32 v4, v108, v109
	s_nop 0
	s_waitcnt lgkmcnt(0)
	v_cvt_pk_bf16_f32 v5, v110, v111
	v_lshl_add_u64 v[38:39], v[36:37], 0, v[0:1]
	s_nop 0
	global_store_dwordx4 v[38:39], v[2:5], off nt
	v_or_b32_e32 v0, s0, v49
	v_lshlrev_b32_e32 v0, 12, v0
	s_waitcnt lgkmcnt(0)
	v_cvt_pk_bf16_f32 v2, v112, v113
	s_nop 0
	s_waitcnt lgkmcnt(0)
	v_cvt_pk_bf16_f32 v3, v114, v115
	s_nop 0
	s_waitcnt lgkmcnt(0)
	v_cvt_pk_bf16_f32 v4, v116, v117
	s_nop 0
	s_waitcnt lgkmcnt(0)
	v_cvt_pk_bf16_f32 v5, v118, v119
	v_lshl_add_u64 v[38:39], v[36:37], 0, v[0:1]
	s_nop 0
	global_store_dwordx4 v[38:39], v[2:5], off nt
	v_or_b32_e32 v0, s0, v50
	v_lshlrev_b32_e32 v0, 12, v0
	s_waitcnt lgkmcnt(0)
	v_cvt_pk_bf16_f32 v2, v120, v121
	s_nop 0
	s_waitcnt lgkmcnt(0)
	v_cvt_pk_bf16_f32 v3, v122, v123
	s_nop 0
	s_waitcnt lgkmcnt(0)
	v_cvt_pk_bf16_f32 v4, v124, v125
	s_nop 0
	s_waitcnt lgkmcnt(0)
	v_cvt_pk_bf16_f32 v5, v126, v127
	v_lshl_add_u64 v[34:35], v[36:37], 0, v[0:1]
	global_store_dwordx4 v[34:35], v[2:5], off nt
	s_waitcnt lgkmcnt(0)

; __device__ __forceinline__ unsigned cvt_pk_bf16(float lo, float hi) { unsigned r; asm volatile("v_cvt_pk_bf16_f32 %0, %1, %2" : "=v"(r) : "v"(lo), "v"(hi)); return r; }
; template <int MAP>
; __device__ __forceinline__ void transpose_item(const float* __restrict__ W, int K, int N, bf16_t* __restrict__ WT, float* scr, int item, int lane) {
;     ...
;     const int c = lane & 7;
; #pragma unroll
;     for (int j = 0; j < 4; ++j) { const int n = (lane >> 3) + 8 * j; const float* s = scr + (8 * c) * 33 + n;
;         u32x4 o; o.x = cvt_pk_bf16(s[0 * 33], s[1 * 33]); o.y = cvt_pk_bf16(s[2 * 33], s[3 * 33]); o.z = cvt_pk_bf16(s[4 * 33], s[5 * 33]); o.w = cvt_pk_bf16(s[6 * 33], s[7 * 33]);
;         if (MAP == 1) *(u32x4*)(WT + (size_t)row_map<MAP>(n0 + n) * K + k0 + 8 * c) = o;
;         else __builtin_nontemporal_store(o, (u32x4*)(WT + (size_t)row_map<MAP>(n0 + n) * K + k0 + 8 * c)); }
.LBB0_255:
	v_lshl_add_u64 v[70:71], v[44:45], 0, s[0:1]
	v_lshl_add_u64 v[72:73], v[42:43], 0, s[0:1]
	v_lshl_add_u64 v[74:75], v[40:41], 0, s[0:1]
	v_lshl_add_u64 v[76:77], v[38:39], 0, s[0:1]
	v_lshl_add_u64 v[78:79], v[36:37], 0, s[0:1]
	v_lshl_add_u64 v[80:81], v[34:35], 0, s[0:1]
	v_lshl_add_u64 v[82:83], v[4:5], 0, s[0:1]
	v_lshl_add_u64 v[84:85], v[2:3], 0, s[0:1]
	global_load_dword v69, v[70:71], off nt
	s_nop 0
	global_load_dword v70, v[72:73], off nt
	global_load_dword v71, v[74:75], off nt
	s_nop 0
	global_load_dword v72, v[76:77], off nt
	global_load_dword v73, v[78:79], off nt
	global_load_dword v74, v[80:81], off nt
	global_load_dword v75, v[82:83], off nt
	s_nop 0
	global_load_dword v76, v[84:85], off nt
	s_add_u32 s0, s0, 0x20000
	s_addc_u32 s1, s1, 0
	v_add_u32_e32 v77, 0x400, v0
	s_cmp_lg_u32 s0, 0x80000
	v_lshl_add_u64 v[130:131], v[44:45], 0, s[0:1]
	v_lshl_add_u64 v[132:133], v[42:43], 0, s[0:1]
	v_lshl_add_u64 v[134:135], v[40:41], 0, s[0:1]
	v_lshl_add_u64 v[136:137], v[38:39], 0, s[0:1]
	v_lshl_add_u64 v[138:139], v[36:37], 0, s[0:1]
	v_lshl_add_u64 v[140:141], v[34:35], 0, s[0:1]
	v_lshl_add_u64 v[142:143], v[4:5], 0, s[0:1]
	v_lshl_add_u64 v[144:145], v[2:3], 0, s[0:1]
	global_load_dword v129, v[130:131], off nt
	s_nop 0
	global_load_dword v130, v[132:133], off nt
	global_load_dword v131, v[134:135], off nt
	s_nop 0
	global_load_dword v132, v[136:137], off nt
	global_load_dword v133, v[138:139], off nt
	global_load_dword v134, v[140:141], off nt
	global_load_dword v135, v[142:143], off nt
	s_nop 0
	global_load_dword v136, v[144:145], off nt
	s_add_u32 s0, s0, 0x20000
	s_addc_u32 s1, s1, 0
	v_add_u32_e32 v137, 0xc40, v0
	s_cmp_lg_u32 s0, 0x80000
	s_waitcnt vmcnt(14)
	ds_write2_b32 v0, v69, v70 offset1:66
	s_waitcnt vmcnt(12)
	ds_write2_b32 v0, v71, v72 offset0:132 offset1:198
	s_waitcnt vmcnt(10)
	ds_write2_b32 v77, v73, v74 offset0:8 offset1:74
	s_waitcnt vmcnt(8)
	ds_write2_b32 v77, v75, v76 offset0:140 offset1:206
	v_add_u32_e32 v0, 0x840, v0
	s_waitcnt vmcnt(6)
	ds_write2_b32 v0, v129, v130 offset1:66
	s_waitcnt vmcnt(4)
	ds_write2_b32 v0, v131, v132 offset0:132 offset1:198
	s_waitcnt vmcnt(2)
	ds_write2_b32 v137, v133, v134 offset0:8 offset1:74
	s_waitcnt vmcnt(0)
	ds_write2_b32 v137, v135, v136 offset0:140 offset1:206
	v_add_u32_e32 v0, 0x840, v0
	s_cbranch_scc1 .LBB0_255
	s_add_i32 s0, s18, 0xffffda00
	s_waitcnt lgkmcnt(0)
	ds_read2_b32 v[96:97], v47 offset1:33
	ds_read2_b32 v[98:99], v47 offset0:66 offset1:99
	ds_read2_b32 v[100:101], v47 offset0:132 offset1:165
	ds_read2_b32 v[102:103], v47 offset0:198 offset1:231
	ds_read2_b32 v[104:105], v47 offset0:8 offset1:41
	ds_read2_b32 v[106:107], v47 offset0:74 offset1:107
	ds_read2_b32 v[108:109], v47 offset0:140 offset1:173
	ds_read2_b32 v[110:111], v47 offset0:206 offset1:239
	ds_read2_b32 v[112:113], v47 offset0:16 offset1:49
	ds_read2_b32 v[114:115], v47 offset0:82 offset1:115
	ds_read2_b32 v[116:117], v47 offset0:148 offset1:181
	ds_read2_b32 v[118:119], v47 offset0:214 offset1:247
	ds_read2_b32 v[120:121], v47 offset0:24 offset1:57
	ds_read2_b32 v[122:123], v47 offset0:90 offset1:123
	ds_read2_b32 v[124:125], v47 offset0:156 offset1:189
	ds_read2_b32 v[126:127], v47 offset0:222 offset1:255
	s_and_b32 s1, s0, 0x1fc0
	s_lshl_b32 s0, s0, 5
	s_nop 0
	s_and_b32 s0, s0, 0x7e0
	s_waitcnt lgkmcnt(0)
	v_cvt_pk_bf16_f32 v2, v96, v97
	s_nop 0
	s_lshl_b32 s60, s1, 1
	v_or_b32_e32 v0, s0, v46
	s_waitcnt lgkmcnt(0)
	v_cvt_pk_bf16_f32 v3, v98, v99
	s_nop 0
	v_lshl_add_u64 v[36:37], v[14:15], 0, s[60:61]
	v_lshlrev_b32_e32 v0, 11, v0
	s_waitcnt lgkmcnt(0)
	v_cvt_pk_bf16_f32 v4, v100, v101
	s_nop 0
	s_waitcnt lgkmcnt(0)
	v_cvt_pk_bf16_f32 v5, v102, v103
	v_lshl_add_u64 v[38:39], v[36:37], 0, v[0:1]
	s_nop 0
	global_store_dwordx4 v[38:39], v[2:5], off nt
	v_or_b32_e32 v0, s0, v48
	v_lshlrev_b32_e32 v0, 11, v0
	s_waitcnt lgkmcnt(0)
	v_cvt_pk_bf16_f32 v2, v104, v105
	s_nop 0
	s_waitcnt lgkmcnt(0)
	v_cvt_pk_bf16_f32 v3, v106, v107
	s_nop 0
	s_waitcnt lgkmcnt(0)
	v_cvt_pk_bf16_f32 v4, v108, v109
	s_nop 0
	s_waitcnt lgkmcnt(0)
	v_cvt_pk_bf16_f32 v5, v110, v111
	v_lshl_add_u64 v[38:39], v[36:37], 0, v[0:1]
	s_nop 0
	global_store_dwordx4 v[38:39], v[2:5], off nt
	v_or_b32_e32 v0, s0, v49
	v_lshlrev_b32_e32 v0, 11, v0
	s_waitcnt lgkmcnt(0)
	v_cvt_pk_bf16_f32 v2, v112, v113
	s_nop 0
	s_waitcnt lgkmcnt(0)
	v_cvt_pk_bf16_f32 v3, v114, v115
	s_nop 0
	s_waitcnt lgkmcnt(0)
	v_cvt_pk_bf16_f32 v4, v116, v117
	s_nop 0
	s_waitcnt lgkmcnt(0)
	v_cvt_pk_bf16_f32 v5, v118, v119
	v_lshl_add_u64 v[38:39], v[36:37], 0, v[0:1]
	s_nop 0
	global_store_dwordx4 v[38:39], v[2:5], off nt
	v_or_b32_e32 v0, s0, v50
	v_lshlrev_b32_e32 v0, 11, v0
	s_waitcnt lgkmcnt(0)
	v_cvt_pk_bf16_f32 v2, v120, v121
	s_nop 0
	s_waitcnt lgkmcnt(0)
	v_cvt_pk_bf16_f32 v3, v122, v123
	s_nop 0
	s_waitcnt lgkmcnt(0)
	v_cvt_pk_bf16_f32 v4, v124, v125
	s_nop 0
	s_waitcnt lgkmcnt(0)
	v_cvt_pk_bf16_f32 v5, v126, v127
	v_lshl_add_u64 v[34:35], v[36:37], 0, v[0:1]
	global_store_dwordx4 v[34:35], v[2:5], off nt
	s_waitcnt lgkmcnt(0)

; __device__ __forceinline__ unsigned cvt_pk_bf16(float lo, float hi) { unsigned r; asm volatile("v_cvt_pk_bf16_f32 %0, %1, %2" : "=v"(r) : "v"(lo), "v"(hi)); return r; }
; template <int MAP>
; __device__ __forceinline__ void transpose_item(const float* __restrict__ W, int K, int N, bf16_t* __restrict__ WT, float* scr, int item, int lane) {
;     ...
;     const int c = lane & 7;
; #pragma unroll
;     for (int j = 0; j < 4; ++j) { const int n = (lane >> 3) + 8 * j; const float* s = scr + (8 * c) * 33 + n;
;         u32x4 o; o.x = cvt_pk_bf16(s[0 * 33], s[1 * 33]); o.y = cvt_pk_bf16(s[2 * 33], s[3 * 33]); o.z = cvt_pk_bf16(s[4 * 33], s[5 * 33]); o.w = cvt_pk_bf16(s[6 * 33], s[7 * 33]);
;         if (MAP == 1) *(u32x4*)(WT + (size_t)row_map<MAP>(n0 + n) * K + k0 + 8 * c) = o;
;         else __builtin_nontemporal_store(o, (u32x4*)(WT + (size_t)row_map<MAP>(n0 + n) * K + k0 + 8 * c)); }
.LBB0_260:
	v_lshl_add_u64 v[70:71], v[44:45], 0, s[0:1]
	v_lshl_add_u64 v[72:73], v[42:43], 0, s[0:1]
	v_lshl_add_u64 v[74:75], v[40:41], 0, s[0:1]
	v_lshl_add_u64 v[76:77], v[38:39], 0, s[0:1]
	v_lshl_add_u64 v[78:79], v[36:37], 0, s[0:1]
	v_lshl_add_u64 v[80:81], v[34:35], 0, s[0:1]
	v_lshl_add_u64 v[82:83], v[4:5], 0, s[0:1]
	v_lshl_add_u64 v[84:85], v[2:3], 0, s[0:1]
	global_load_dword v69, v[70:71], off nt
	s_nop 0
	global_load_dword v70, v[72:73], off nt
	global_load_dword v71, v[74:75], off nt
	s_nop 0
	global_load_dword v72, v[76:77], off nt
	global_load_dword v73, v[78:79], off nt
	global_load_dword v74, v[80:81], off nt
	global_load_dword v75, v[82:83], off nt
	s_nop 0
	global_load_dword v76, v[84:85], off nt
	s_add_u32 s0, s0, 0x20000
	s_addc_u32 s1, s1, 0
	v_add_u32_e32 v77, 0x400, v0
	s_cmp_lg_u32 s0, 0x80000
	v_lshl_add_u64 v[130:131], v[44:45], 0, s[0:1]
	v_lshl_add_u64 v[132:133], v[42:43], 0, s[0:1]
	v_lshl_add_u64 v[134:135], v[40:41], 0, s[0:1]
	v_lshl_add_u64 v[136:137], v[38:39], 0, s[0:1]
	v_lshl_add_u64 v[138:139], v[36:37], 0, s[0:1]
	v_lshl_add_u64 v[140:141], v[34:35], 0, s[0:1]
	v_lshl_add_u64 v[142:143], v[4:5], 0, s[0:1]
	v_lshl_add_u64 v[144:145], v[2:3], 0, s[0:1]
	global_load_dword v129, v[130:131], off nt
	s_nop 0
	global_load_dword v130, v[132:133], off nt
	global_load_dword v131, v[134:135], off nt
	s_nop 0
	global_load_dword v132, v[136:137], off nt
	global_load_dword v133, v[138:139], off nt
	global_load_dword v134, v[140:141], off nt
	global_load_dword v135, v[142:143], off nt
	s_nop 0
	global_load_dword v136, v[144:145], off nt
	s_add_u32 s0, s0, 0x20000
	s_addc_u32 s1, s1, 0
	v_add_u32_e32 v137, 0xc40, v0
	s_cmp_lg_u32 s0, 0x80000
	s_waitcnt vmcnt(14)
	ds_write2_b32 v0, v69, v70 offset1:66
	s_waitcnt vmcnt(12)
	ds_write2_b32 v0, v71, v72 offset0:132 offset1:198
	s_waitcnt vmcnt(10)
	ds_write2_b32 v77, v73, v74 offset0:8 offset1:74
	s_waitcnt vmcnt(8)
	ds_write2_b32 v77, v75, v76 offset0:140 offset1:206
	v_add_u32_e32 v0, 0x840, v0
	s_waitcnt vmcnt(6)
	ds_write2_b32 v0, v129, v130 offset1:66
	s_waitcnt vmcnt(4)
	ds_write2_b32 v0, v131, v132 offset0:132 offset1:198
	s_waitcnt vmcnt(2)
	ds_write2_b32 v137, v133, v134 offset0:8 offset1:74
	s_waitcnt vmcnt(0)
	ds_write2_b32 v137, v135, v136 offset0:140 offset1:206
	v_add_u32_e32 v0, 0x840, v0
	s_cbranch_scc1 .LBB0_260
	s_add_i32 s0, s18, 0xffffde00
	s_waitcnt lgkmcnt(0)
	ds_read2_b32 v[96:97], v47 offset1:33
	ds_read2_b32 v[98:99], v47 offset0:66 offset1:99
	ds_read2_b32 v[100:101], v47 offset0:132 offset1:165
	ds_read2_b32 v[102:103], v47 offset0:198 offset1:231
	ds_read2_b32 v[104:105], v47 offset0:8 offset1:41
	ds_read2_b32 v[106:107], v47 offset0:74 offset1:107
	ds_read2_b32 v[108:109], v47 offset0:140 offset1:173
	ds_read2_b32 v[110:111], v47 offset0:206 offset1:239
	ds_read2_b32 v[112:113], v47 offset0:16 offset1:49
	ds_read2_b32 v[114:115], v47 offset0:82 offset1:115
	ds_read2_b32 v[116:117], v47 offset0:148 offset1:181
	ds_read2_b32 v[118:119], v47 offset0:214 offset1:247
	ds_read2_b32 v[120:121], v47 offset0:24 offset1:57
	ds_read2_b32 v[122:123], v47 offset0:90 offset1:123
	ds_read2_b32 v[124:125], v47 offset0:156 offset1:189
	ds_read2_b32 v[126:127], v47 offset0:222 offset1:255
	s_and_b32 s1, s0, 0x1fc0
	s_lshl_b32 s0, s0, 5
	s_nop 0
	s_and_b32 s0, s0, 0x7e0
	s_waitcnt lgkmcnt(0)
	v_cvt_pk_bf16_f32 v2, v96, v97
	s_nop 0
	s_lshl_b32 s60, s1, 1
	v_or_b32_e32 v0, s0, v46
	s_waitcnt lgkmcnt(0)
	v_cvt_pk_bf16_f32 v3, v98, v99
	s_nop 0
	v_lshl_add_u64 v[36:37], v[16:17], 0, s[60:61]
	v_lshlrev_b32_e32 v0, 11, v0
	s_waitcnt lgkmcnt(0)
	v_cvt_pk_bf16_f32 v4, v100, v101
	s_nop 0
	s_waitcnt lgkmcnt(0)
	v_cvt_pk_bf16_f32 v5, v102, v103
	v_lshl_add_u64 v[38:39], v[36:37], 0, v[0:1]
	s_nop 0
	global_store_dwordx4 v[38:39], v[2:5], off nt
	v_or_b32_e32 v0, s0, v48
	v_lshlrev_b32_e32 v0, 11, v0
	s_waitcnt lgkmcnt(0)
	v_cvt_pk_bf16_f32 v2, v104, v105
	s_nop 0
	s_waitcnt lgkmcnt(0)
	v_cvt_pk_bf16_f32 v3, v106, v107
	s_nop 0
	s_waitcnt lgkmcnt(0)
	v_cvt_pk_bf16_f32 v4, v108, v109
	s_nop 0
	s_waitcnt lgkmcnt(0)
	v_cvt_pk_bf16_f32 v5, v110, v111
	v_lshl_add_u64 v[38:39], v[36:37], 0, v[0:1]
	s_nop 0
	global_store_dwordx4 v[38:39], v[2:5], off nt
	v_or_b32_e32 v0, s0, v49
	v_lshlrev_b32_e32 v0, 11, v0
	s_waitcnt lgkmcnt(0)
	v_cvt_pk_bf16_f32 v2, v112, v113
	s_nop 0
	s_waitcnt lgkmcnt(0)
	v_cvt_pk_bf16_f32 v3, v114, v115
	s_nop 0
	s_waitcnt lgkmcnt(0)
	v_cvt_pk_bf16_f32 v4, v116, v117
	s_nop 0
	s_waitcnt lgkmcnt(0)
	v_cvt_pk_bf16_f32 v5, v118, v119
	v_lshl_add_u64 v[38:39], v[36:37], 0, v[0:1]
	s_nop 0
	global_store_dwordx4 v[38:39], v[2:5], off nt
	v_or_b32_e32 v0, s0, v50
	v_lshlrev_b32_e32 v0, 11, v0
	s_waitcnt lgkmcnt(0)
	v_cvt_pk_bf16_f32 v2, v120, v121
	s_nop 0
	s_waitcnt lgkmcnt(0)
	v_cvt_pk_bf16_f32 v3, v122, v123
	s_nop 0
	s_waitcnt lgkmcnt(0)
	v_cvt_pk_bf16_f32 v4, v124, v125
	s_nop 0
	s_waitcnt lgkmcnt(0)
	v_cvt_pk_bf16_f32 v5, v126, v127
	v_lshl_add_u64 v[34:35], v[36:37], 0, v[0:1]
	global_store_dwordx4 v[34:35], v[2:5], off nt
	s_waitcnt lgkmcnt(0)
